# v56 + de-serialized G2a epilogue (bias, gate and residual loads issued first, counted waits)
# speedup vs baseline: 1.0059x; 1.0059x over previous
.LBB1_90:
	s_lshl_b32 s19, s18, 8
	s_add_i32 s19, s19, 0x80
	s_min_u32 s19, s19, 0x780
	s_add_u32 s40, s8, s19
	s_addc_u32 s41, s9, 0
	s_add_u32 s42, s10, s19
	s_addc_u32 s43, s11, 0
	ds_read_b128 v[142:145], v234 offset:0
	ds_read_b128 v[146:149], v234 offset:2048
	ds_read_b128 v[150:153], v234 offset:4096
	ds_read_b128 v[154:157], v234 offset:6144
	ds_read_b128 v[130:133], v232 offset:0
	ds_read_b128 v[134:137], v232 offset:2048
	ds_read_b128 v[138:141], v232 offset:4096
	ds_read_b128 v[216:219], v235 offset:0
	ds_read_b128 v[220:223], v235 offset:2048
	ds_read_b128 v[224:227], v235 offset:4096
	ds_read_b128 v[228:231], v235 offset:6144
	ds_read_b128 v[188:191], v233 offset:0
	ds_read_b128 v[192:195], v233 offset:2048
	ds_read_b128 v[196:199], v233 offset:4096
	s_waitcnt lgkmcnt(9)
	s_add_i32 m0, s16, 0x7010
	s_nop 0
	v_mfma_f32_16x16x32_bf16 v[72:75], v[142:145], v[130:133], v[72:75]
	global_load_lds_dwordx4 v238, s[40:41]
	s_add_i32 m0, s16, 0x7410
	s_add_u32 s12, s40, 0x4000
	s_addc_u32 s13, s41, 0
	v_mfma_f32_16x16x32_bf16 v[40:43], v[146:149], v[130:133], v[40:43]
	global_load_lds_dwordx4 v239, s[12:13]
	v_mfma_f32_16x16x32_bf16 v[36:39], v[150:153], v[130:133], v[36:39]
	v_mfma_f32_16x16x32_bf16 v[32:35], v[154:157], v[130:133], v[32:35]
	s_waitcnt lgkmcnt(8)
	s_add_i32 m0, s16, 0x7810
	s_add_u32 s12, s40, 0x8000
	s_addc_u32 s13, s41, 0
	v_mfma_f32_16x16x32_bf16 v[28:31], v[142:145], v[134:137], v[28:31]
	v_mfma_f32_16x16x32_bf16 v[24:27], v[146:149], v[134:137], v[24:27]
	global_load_lds_dwordx4 v238, s[12:13]
	v_mfma_f32_16x16x32_bf16 v[20:23], v[150:153], v[134:137], v[20:23]
	v_mfma_f32_16x16x32_bf16 v[16:19], v[154:157], v[134:137], v[16:19]
	s_waitcnt lgkmcnt(7)
	s_add_i32 m0, s17, 0xa010
	s_nop 0
	v_mfma_f32_16x16x32_bf16 v[12:15], v[142:145], v[138:141], v[12:15]
	v_mfma_f32_16x16x32_bf16 v[8:11], v[146:149], v[138:141], v[8:11]
	global_load_lds_dwordx4 v236, s[42:43]
	v_mfma_f32_16x16x32_bf16 v[4:7], v[150:153], v[138:141], v[4:7]
	v_mfma_f32_16x16x32_bf16 v[0:3], v[154:157], v[138:141], v[0:3]
	s_waitcnt lgkmcnt(2)
	s_add_i32 m0, s17, 0xa410
	s_add_u32 s12, s42, 0x4000
	s_addc_u32 s13, s43, 0
	v_mfma_f32_16x16x32_bf16 v[72:75], v[216:219], v[188:191], v[72:75]
	v_mfma_f32_16x16x32_bf16 v[40:43], v[220:223], v[188:191], v[40:43]
	global_load_lds_dwordx4 v237, s[12:13]
	v_mfma_f32_16x16x32_bf16 v[36:39], v[224:227], v[188:191], v[36:39]
	v_mfma_f32_16x16x32_bf16 v[32:35], v[228:231], v[188:191], v[32:35]
	s_waitcnt lgkmcnt(1)
	s_add_i32 m0, s17, 0xa810
	s_add_u32 s12, s42, 0x8000
	s_addc_u32 s13, s43, 0
	v_mfma_f32_16x16x32_bf16 v[28:31], v[216:219], v[192:195], v[28:31]
	v_mfma_f32_16x16x32_bf16 v[24:27], v[220:223], v[192:195], v[24:27]
	global_load_lds_dwordx4 v236, s[12:13]
	v_mfma_f32_16x16x32_bf16 v[20:23], v[224:227], v[192:195], v[20:23]
	v_mfma_f32_16x16x32_bf16 v[16:19], v[228:231], v[192:195], v[16:19]
	s_waitcnt lgkmcnt(0)
	s_add_i32 m0, s17, 0xac10
	s_add_u32 s12, s42, 0xc000
	s_addc_u32 s13, s43, 0
	v_mfma_f32_16x16x32_bf16 v[12:15], v[216:219], v[196:199], v[12:15]
	v_mfma_f32_16x16x32_bf16 v[8:11], v[220:223], v[196:199], v[8:11]
	global_load_lds_dwordx4 v237, s[12:13]
	v_mfma_f32_16x16x32_bf16 v[4:7], v[224:227], v[196:199], v[4:7]
	v_mfma_f32_16x16x32_bf16 v[0:3], v[228:231], v[196:199], v[0:3]
	s_waitcnt vmcnt(0)
	s_barrier
	s_lshl_b32 s19, s18, 8
	s_add_i32 s19, s19, 0x100
	s_min_u32 s19, s19, 0x780
	s_add_u32 s40, s8, s19
	s_addc_u32 s41, s9, 0
	s_add_u32 s42, s10, s19
	s_addc_u32 s43, s11, 0
	ds_read_b128 v[142:145], v234 offset:28672
	ds_read_b128 v[146:149], v234 offset:30720
	ds_read_b128 v[150:153], v234 offset:32768
	ds_read_b128 v[154:157], v234 offset:34816
	ds_read_b128 v[130:133], v232 offset:28672
	ds_read_b128 v[134:137], v232 offset:30720
	ds_read_b128 v[138:141], v232 offset:32768
	ds_read_b128 v[216:219], v235 offset:28672
	ds_read_b128 v[220:223], v235 offset:30720
	ds_read_b128 v[224:227], v235 offset:32768
	ds_read_b128 v[228:231], v235 offset:34816
	ds_read_b128 v[188:191], v233 offset:28672
	ds_read_b128 v[192:195], v233 offset:30720
	ds_read_b128 v[196:199], v233 offset:32768
	s_waitcnt lgkmcnt(9)
	s_add_i32 m0, s16, 0x10
	s_nop 0
	v_mfma_f32_16x16x32_bf16 v[72:75], v[142:145], v[130:133], v[72:75]
	global_load_lds_dwordx4 v238, s[40:41]
	s_add_i32 m0, s16, 0x410
	s_add_u32 s12, s40, 0x4000
	s_addc_u32 s13, s41, 0
	v_mfma_f32_16x16x32_bf16 v[40:43], v[146:149], v[130:133], v[40:43]
	global_load_lds_dwordx4 v239, s[12:13]
	v_mfma_f32_16x16x32_bf16 v[36:39], v[150:153], v[130:133], v[36:39]
	v_mfma_f32_16x16x32_bf16 v[32:35], v[154:157], v[130:133], v[32:35]
	s_waitcnt lgkmcnt(8)
	s_add_i32 m0, s16, 0x810
	s_add_u32 s12, s40, 0x8000
	s_addc_u32 s13, s41, 0
	v_mfma_f32_16x16x32_bf16 v[28:31], v[142:145], v[134:137], v[28:31]
	v_mfma_f32_16x16x32_bf16 v[24:27], v[146:149], v[134:137], v[24:27]
	global_load_lds_dwordx4 v238, s[12:13]
	v_mfma_f32_16x16x32_bf16 v[20:23], v[150:153], v[134:137], v[20:23]
	v_mfma_f32_16x16x32_bf16 v[16:19], v[154:157], v[134:137], v[16:19]
	s_waitcnt lgkmcnt(7)
	s_add_i32 m0, s17, 0x3010
	s_nop 0
	v_mfma_f32_16x16x32_bf16 v[12:15], v[142:145], v[138:141], v[12:15]
	v_mfma_f32_16x16x32_bf16 v[8:11], v[146:149], v[138:141], v[8:11]
	global_load_lds_dwordx4 v236, s[42:43]
	v_mfma_f32_16x16x32_bf16 v[4:7], v[150:153], v[138:141], v[4:7]
	v_mfma_f32_16x16x32_bf16 v[0:3], v[154:157], v[138:141], v[0:3]
	s_waitcnt lgkmcnt(2)
	s_add_i32 m0, s17, 0x3410
	s_add_u32 s12, s42, 0x4000
	s_addc_u32 s13, s43, 0
	v_mfma_f32_16x16x32_bf16 v[72:75], v[216:219], v[188:191], v[72:75]
	v_mfma_f32_16x16x32_bf16 v[40:43], v[220:223], v[188:191], v[40:43]
	global_load_lds_dwordx4 v237, s[12:13]
	v_mfma_f32_16x16x32_bf16 v[36:39], v[224:227], v[188:191], v[36:39]
	v_mfma_f32_16x16x32_bf16 v[32:35], v[228:231], v[188:191], v[32:35]
	s_waitcnt lgkmcnt(1)
	s_add_i32 m0, s17, 0x3810
	s_add_u32 s12, s42, 0x8000
	s_addc_u32 s13, s43, 0
	v_mfma_f32_16x16x32_bf16 v[28:31], v[216:219], v[192:195], v[28:31]
	v_mfma_f32_16x16x32_bf16 v[24:27], v[220:223], v[192:195], v[24:27]
	global_load_lds_dwordx4 v236, s[12:13]
	v_mfma_f32_16x16x32_bf16 v[20:23], v[224:227], v[192:195], v[20:23]
	v_mfma_f32_16x16x32_bf16 v[16:19], v[228:231], v[192:195], v[16:19]
	s_waitcnt lgkmcnt(0)
	s_add_i32 m0, s17, 0x3c10
	s_add_u32 s12, s42, 0xc000
	s_addc_u32 s13, s43, 0
	v_mfma_f32_16x16x32_bf16 v[12:15], v[216:219], v[196:199], v[12:15]
	v_mfma_f32_16x16x32_bf16 v[8:11], v[220:223], v[196:199], v[8:11]
	global_load_lds_dwordx4 v237, s[12:13]
	v_mfma_f32_16x16x32_bf16 v[4:7], v[224:227], v[196:199], v[4:7]
	v_mfma_f32_16x16x32_bf16 v[0:3], v[228:231], v[196:199], v[0:3]
	s_waitcnt vmcnt(0)
	s_barrier
	s_add_i32 s18, s18, 1
	s_cmp_eq_u32 s18, 8
	s_cbranch_scc0 .LBB1_90
	s_setprio 0
	s_waitcnt vmcnt(0)
	v_readlane_b32 s6, v241, 34
	v_readlane_b32 s7, v241, 35
	s_load_dwordx2 s[12:13], s[0:1], 0x168
	v_and_b32_e32 v154, 15, v168
	v_lshrrev_b32_e32 v155, 4, v168
	v_lshrrev_b32_e32 v156, 7, v162
	v_bfe_u32 v157, v162, 6, 1
	v_mul_u32_u24_e32 v156, 48, v156
	v_add3_u32 v156, v156, v154, s5
	v_lshlrev_b32_e32 v157, 6, v157
	v_lshl_add_u32 v157, v155, 2, v157
	v_add_u32_e32 v157, s4, v157
	v_lshlrev_b32_e32 v53, 2, v157
	v_lshlrev_b32_e32 v158, 1, v157
	v_lshl_add_u32 v44, v156, 14, v158
	v_lshl_add_u32 v50, v156, 11, v158
	v_lshl_add_u32 v47, v156, 12, v53
	v_add_u32_e32 v156, 16, v156
	v_lshlrev_b32_e32 v158, 1, v157
	v_lshl_add_u32 v45, v156, 14, v158
	v_lshl_add_u32 v51, v156, 11, v158
	v_lshl_add_u32 v48, v156, 12, v53
	v_add_u32_e32 v156, 16, v156
	v_lshlrev_b32_e32 v158, 1, v157
	v_lshl_add_u32 v46, v156, 14, v158
	v_lshl_add_u32 v52, v156, 11, v158
	v_lshl_add_u32 v49, v156, 12, v53
	s_add_u32 s8, s6, 0
	s_addc_u32 s9, s7, 0
	s_add_u32 s10, s76, 0x3000
	s_addc_u32 s11, s77, 0
	global_load_dwordx4 v[54:57], v53, s[8:9] offset:0
	global_load_dwordx4 v[58:61], v53, s[8:9] offset:64
	global_load_dwordx4 v[62:65], v53, s[8:9] offset:128
	global_load_dwordx4 v[66:69], v53, s[8:9] offset:192
	global_load_dwordx2 v[188:189], v44, s[10:11] offset:0
	global_load_dwordx4 v[100:103], v47, s[72:73] offset:0
	global_load_dwordx2 v[190:191], v44, s[10:11] offset:32
	global_load_dwordx4 v[104:107], v47, s[72:73] offset:64
	global_load_dwordx2 v[192:193], v44, s[10:11] offset:64
	global_load_dwordx4 v[108:111], v47, s[72:73] offset:128
	global_load_dwordx2 v[194:195], v44, s[10:11] offset:96
	global_load_dwordx4 v[112:115], v47, s[72:73] offset:192
	global_load_dwordx2 v[196:197], v45, s[10:11] offset:0
	global_load_dwordx4 v[116:119], v48, s[72:73] offset:0
	global_load_dwordx2 v[198:199], v45, s[10:11] offset:32
	global_load_dwordx4 v[120:123], v48, s[72:73] offset:64
	global_load_dwordx2 v[200:201], v45, s[10:11] offset:64
	global_load_dwordx4 v[232:235], v48, s[72:73] offset:128
	global_load_dwordx2 v[202:203], v45, s[10:11] offset:96
	global_load_dwordx4 v[130:133], v48, s[72:73] offset:192
	global_load_dwordx2 v[204:205], v46, s[10:11] offset:0
	global_load_dwordx4 v[134:137], v49, s[72:73] offset:0
	global_load_dwordx2 v[206:207], v46, s[10:11] offset:32
	global_load_dwordx4 v[138:141], v49, s[72:73] offset:64
	global_load_dwordx2 v[208:209], v46, s[10:11] offset:64
	global_load_dwordx4 v[142:145], v49, s[72:73] offset:128
	global_load_dwordx2 v[210:211], v46, s[10:11] offset:96
	global_load_dwordx4 v[146:149], v49, s[72:73] offset:192
	s_add_i32 s2, s2, 1
	v_readlane_b32 s55, v241, 23
	s_waitcnt lgkmcnt(0)
	s_waitcnt vmcnt(22)
	v_lshlrev_b32_e32 v150, 16, v188
	v_and_b32_e32 v151, 0xffff0000, v188
	v_lshlrev_b32_e32 v152, 16, v189
	v_and_b32_e32 v153, 0xffff0000, v189
	v_pk_add_f32 v[150:151], v[54:55], v[150:151]
	v_pk_add_f32 v[152:153], v[56:57], v[152:153]
	s_nop 0
	v_mul_f32_e32 v150, 0xbfb8aa3b, v150
	v_mul_f32_e32 v151, 0xbfb8aa3b, v151
	v_mul_f32_e32 v152, 0xbfb8aa3b, v152
	v_mul_f32_e32 v153, 0xbfb8aa3b, v153
	v_exp_f32_e32 v150, v150
	v_exp_f32_e32 v151, v151
	v_exp_f32_e32 v152, v152
	v_exp_f32_e32 v153, v153
	v_add_f32_e32 v150, 1.0, v150
	v_add_f32_e32 v151, 1.0, v151
	v_add_f32_e32 v152, 1.0, v152
	v_add_f32_e32 v153, 1.0, v153
	v_rcp_f32_e32 v150, v150
	v_rcp_f32_e32 v151, v151
	v_rcp_f32_e32 v152, v152
	v_rcp_f32_e32 v153, v153
	v_pk_fma_f32 v[72:73], v[72:73], v[150:151], v[100:101]
	v_pk_fma_f32 v[74:75], v[74:75], v[152:153], v[102:103]
	s_nop 0
	v_cvt_pk_bf16_f32 v72, v72, v73
	v_cvt_pk_bf16_f32 v73, v74, v75
	global_store_dwordx2 v50, v[72:73], s[12:13] offset:0
	s_waitcnt vmcnt(20)
	v_lshlrev_b32_e32 v150, 16, v190
	v_and_b32_e32 v151, 0xffff0000, v190
	v_lshlrev_b32_e32 v152, 16, v191
	v_and_b32_e32 v153, 0xffff0000, v191
	v_pk_add_f32 v[150:151], v[58:59], v[150:151]
	v_pk_add_f32 v[152:153], v[60:61], v[152:153]
	s_nop 0
	v_mul_f32_e32 v150, 0xbfb8aa3b, v150
	v_mul_f32_e32 v151, 0xbfb8aa3b, v151
	v_mul_f32_e32 v152, 0xbfb8aa3b, v152
	v_mul_f32_e32 v153, 0xbfb8aa3b, v153
	v_exp_f32_e32 v150, v150
	v_exp_f32_e32 v151, v151
	v_exp_f32_e32 v152, v152
	v_exp_f32_e32 v153, v153
	v_add_f32_e32 v150, 1.0, v150
	v_add_f32_e32 v151, 1.0, v151
	v_add_f32_e32 v152, 1.0, v152
	v_add_f32_e32 v153, 1.0, v153
	v_rcp_f32_e32 v150, v150
	v_rcp_f32_e32 v151, v151
	v_rcp_f32_e32 v152, v152
	v_rcp_f32_e32 v153, v153
	v_pk_fma_f32 v[40:41], v[40:41], v[150:151], v[104:105]
	v_pk_fma_f32 v[42:43], v[42:43], v[152:153], v[106:107]
	s_nop 0
	v_cvt_pk_bf16_f32 v40, v40, v41
	v_cvt_pk_bf16_f32 v41, v42, v43
	global_store_dwordx2 v50, v[40:41], s[12:13] offset:32
	s_waitcnt vmcnt(18)
	v_lshlrev_b32_e32 v150, 16, v192
	v_and_b32_e32 v151, 0xffff0000, v192
	v_lshlrev_b32_e32 v152, 16, v193
	v_and_b32_e32 v153, 0xffff0000, v193
	v_pk_add_f32 v[150:151], v[62:63], v[150:151]
	v_pk_add_f32 v[152:153], v[64:65], v[152:153]
	s_nop 0
	v_mul_f32_e32 v150, 0xbfb8aa3b, v150
	v_mul_f32_e32 v151, 0xbfb8aa3b, v151
	v_mul_f32_e32 v152, 0xbfb8aa3b, v152
	v_mul_f32_e32 v153, 0xbfb8aa3b, v153
	v_exp_f32_e32 v150, v150
	v_exp_f32_e32 v151, v151
	v_exp_f32_e32 v152, v152
	v_exp_f32_e32 v153, v153
	v_add_f32_e32 v150, 1.0, v150
	v_add_f32_e32 v151, 1.0, v151
	v_add_f32_e32 v152, 1.0, v152
	v_add_f32_e32 v153, 1.0, v153
	v_rcp_f32_e32 v150, v150
	v_rcp_f32_e32 v151, v151
	v_rcp_f32_e32 v152, v152
	v_rcp_f32_e32 v153, v153
	v_pk_fma_f32 v[36:37], v[36:37], v[150:151], v[108:109]
	v_pk_fma_f32 v[38:39], v[38:39], v[152:153], v[110:111]
	s_nop 0
	v_cvt_pk_bf16_f32 v36, v36, v37
	v_cvt_pk_bf16_f32 v37, v38, v39
	global_store_dwordx2 v50, v[36:37], s[12:13] offset:64
	s_waitcnt vmcnt(16)
	v_lshlrev_b32_e32 v150, 16, v194
	v_and_b32_e32 v151, 0xffff0000, v194
	v_lshlrev_b32_e32 v152, 16, v195
	v_and_b32_e32 v153, 0xffff0000, v195
	v_pk_add_f32 v[150:151], v[66:67], v[150:151]
	v_pk_add_f32 v[152:153], v[68:69], v[152:153]
	s_nop 0
	v_mul_f32_e32 v150, 0xbfb8aa3b, v150
	v_mul_f32_e32 v151, 0xbfb8aa3b, v151
	v_mul_f32_e32 v152, 0xbfb8aa3b, v152
	v_mul_f32_e32 v153, 0xbfb8aa3b, v153
	v_exp_f32_e32 v150, v150
	v_exp_f32_e32 v151, v151
	v_exp_f32_e32 v152, v152
	v_exp_f32_e32 v153, v153
	v_add_f32_e32 v150, 1.0, v150
	v_add_f32_e32 v151, 1.0, v151
	v_add_f32_e32 v152, 1.0, v152
	v_add_f32_e32 v153, 1.0, v153
	v_rcp_f32_e32 v150, v150
	v_rcp_f32_e32 v151, v151
	v_rcp_f32_e32 v152, v152
	v_rcp_f32_e32 v153, v153
	v_pk_fma_f32 v[32:33], v[32:33], v[150:151], v[112:113]
	v_pk_fma_f32 v[34:35], v[34:35], v[152:153], v[114:115]
	s_nop 0
	v_cvt_pk_bf16_f32 v32, v32, v33
	v_cvt_pk_bf16_f32 v33, v34, v35
	global_store_dwordx2 v50, v[32:33], s[12:13] offset:96
	s_waitcnt vmcnt(14)
	v_lshlrev_b32_e32 v150, 16, v196
	v_and_b32_e32 v151, 0xffff0000, v196
	v_lshlrev_b32_e32 v152, 16, v197
	v_and_b32_e32 v153, 0xffff0000, v197
	v_pk_add_f32 v[150:151], v[54:55], v[150:151]
	v_pk_add_f32 v[152:153], v[56:57], v[152:153]
	s_nop 0
	v_mul_f32_e32 v150, 0xbfb8aa3b, v150
	v_mul_f32_e32 v151, 0xbfb8aa3b, v151
	v_mul_f32_e32 v152, 0xbfb8aa3b, v152
	v_mul_f32_e32 v153, 0xbfb8aa3b, v153
	v_exp_f32_e32 v150, v150
	v_exp_f32_e32 v151, v151
	v_exp_f32_e32 v152, v152
	v_exp_f32_e32 v153, v153
	v_add_f32_e32 v150, 1.0, v150
	v_add_f32_e32 v151, 1.0, v151
	v_add_f32_e32 v152, 1.0, v152
	v_add_f32_e32 v153, 1.0, v153
	v_rcp_f32_e32 v150, v150
	v_rcp_f32_e32 v151, v151
	v_rcp_f32_e32 v152, v152
	v_rcp_f32_e32 v153, v153
	v_pk_fma_f32 v[28:29], v[28:29], v[150:151], v[116:117]
	v_pk_fma_f32 v[30:31], v[30:31], v[152:153], v[118:119]
	s_nop 0
	v_cvt_pk_bf16_f32 v28, v28, v29
	v_cvt_pk_bf16_f32 v29, v30, v31
	global_store_dwordx2 v51, v[28:29], s[12:13] offset:0
	s_waitcnt vmcnt(12)
	v_lshlrev_b32_e32 v150, 16, v198
	v_and_b32_e32 v151, 0xffff0000, v198
	v_lshlrev_b32_e32 v152, 16, v199
	v_and_b32_e32 v153, 0xffff0000, v199
	v_pk_add_f32 v[150:151], v[58:59], v[150:151]
	v_pk_add_f32 v[152:153], v[60:61], v[152:153]
	s_nop 0
	v_mul_f32_e32 v150, 0xbfb8aa3b, v150
	v_mul_f32_e32 v151, 0xbfb8aa3b, v151
	v_mul_f32_e32 v152, 0xbfb8aa3b, v152
	v_mul_f32_e32 v153, 0xbfb8aa3b, v153
	v_exp_f32_e32 v150, v150
	v_exp_f32_e32 v151, v151
	v_exp_f32_e32 v152, v152
	v_exp_f32_e32 v153, v153
	v_add_f32_e32 v150, 1.0, v150
	v_add_f32_e32 v151, 1.0, v151
	v_add_f32_e32 v152, 1.0, v152
	v_add_f32_e32 v153, 1.0, v153
	v_rcp_f32_e32 v150, v150
	v_rcp_f32_e32 v151, v151
	v_rcp_f32_e32 v152, v152
	v_rcp_f32_e32 v153, v153
	v_pk_fma_f32 v[24:25], v[24:25], v[150:151], v[120:121]
	v_pk_fma_f32 v[26:27], v[26:27], v[152:153], v[122:123]
	s_nop 0
	v_cvt_pk_bf16_f32 v24, v24, v25
	v_cvt_pk_bf16_f32 v25, v26, v27
	global_store_dwordx2 v51, v[24:25], s[12:13] offset:32
	s_waitcnt vmcnt(10)
	v_lshlrev_b32_e32 v150, 16, v200
	v_and_b32_e32 v151, 0xffff0000, v200
	v_lshlrev_b32_e32 v152, 16, v201
	v_and_b32_e32 v153, 0xffff0000, v201
	v_pk_add_f32 v[150:151], v[62:63], v[150:151]
	v_pk_add_f32 v[152:153], v[64:65], v[152:153]
	s_nop 0
	v_mul_f32_e32 v150, 0xbfb8aa3b, v150
	v_mul_f32_e32 v151, 0xbfb8aa3b, v151
	v_mul_f32_e32 v152, 0xbfb8aa3b, v152
	v_mul_f32_e32 v153, 0xbfb8aa3b, v153
	v_exp_f32_e32 v150, v150
	v_exp_f32_e32 v151, v151
	v_exp_f32_e32 v152, v152
	v_exp_f32_e32 v153, v153
	v_add_f32_e32 v150, 1.0, v150
	v_add_f32_e32 v151, 1.0, v151
	v_add_f32_e32 v152, 1.0, v152
	v_add_f32_e32 v153, 1.0, v153
	v_rcp_f32_e32 v150, v150
	v_rcp_f32_e32 v151, v151
	v_rcp_f32_e32 v152, v152
	v_rcp_f32_e32 v153, v153
	v_pk_fma_f32 v[20:21], v[20:21], v[150:151], v[232:233]
	v_pk_fma_f32 v[22:23], v[22:23], v[152:153], v[234:235]
	s_nop 0
	v_cvt_pk_bf16_f32 v20, v20, v21
	v_cvt_pk_bf16_f32 v21, v22, v23
	global_store_dwordx2 v51, v[20:21], s[12:13] offset:64
	s_waitcnt vmcnt(8)
	v_lshlrev_b32_e32 v150, 16, v202
	v_and_b32_e32 v151, 0xffff0000, v202
	v_lshlrev_b32_e32 v152, 16, v203
	v_and_b32_e32 v153, 0xffff0000, v203
	v_pk_add_f32 v[150:151], v[66:67], v[150:151]
	v_pk_add_f32 v[152:153], v[68:69], v[152:153]
	s_nop 0
	v_mul_f32_e32 v150, 0xbfb8aa3b, v150
	v_mul_f32_e32 v151, 0xbfb8aa3b, v151
	v_mul_f32_e32 v152, 0xbfb8aa3b, v152
	v_mul_f32_e32 v153, 0xbfb8aa3b, v153
	v_exp_f32_e32 v150, v150
	v_exp_f32_e32 v151, v151
	v_exp_f32_e32 v152, v152
	v_exp_f32_e32 v153, v153
	v_add_f32_e32 v150, 1.0, v150
	v_add_f32_e32 v151, 1.0, v151
	v_add_f32_e32 v152, 1.0, v152
	v_add_f32_e32 v153, 1.0, v153
	v_rcp_f32_e32 v150, v150
	v_rcp_f32_e32 v151, v151
	v_rcp_f32_e32 v152, v152
	v_rcp_f32_e32 v153, v153
	v_pk_fma_f32 v[16:17], v[16:17], v[150:151], v[130:131]
	v_pk_fma_f32 v[18:19], v[18:19], v[152:153], v[132:133]
	s_nop 0
	v_cvt_pk_bf16_f32 v16, v16, v17
	v_cvt_pk_bf16_f32 v17, v18, v19
	global_store_dwordx2 v51, v[16:17], s[12:13] offset:96
	s_waitcnt vmcnt(6)
	v_lshlrev_b32_e32 v150, 16, v204
	v_and_b32_e32 v151, 0xffff0000, v204
	v_lshlrev_b32_e32 v152, 16, v205
	v_and_b32_e32 v153, 0xffff0000, v205
	v_pk_add_f32 v[150:151], v[54:55], v[150:151]
	v_pk_add_f32 v[152:153], v[56:57], v[152:153]
	s_nop 0
	v_mul_f32_e32 v150, 0xbfb8aa3b, v150
	v_mul_f32_e32 v151, 0xbfb8aa3b, v151
	v_mul_f32_e32 v152, 0xbfb8aa3b, v152
	v_mul_f32_e32 v153, 0xbfb8aa3b, v153
	v_exp_f32_e32 v150, v150
	v_exp_f32_e32 v151, v151
	v_exp_f32_e32 v152, v152
	v_exp_f32_e32 v153, v153
	v_add_f32_e32 v150, 1.0, v150
	v_add_f32_e32 v151, 1.0, v151
	v_add_f32_e32 v152, 1.0, v152
	v_add_f32_e32 v153, 1.0, v153
	v_rcp_f32_e32 v150, v150
	v_rcp_f32_e32 v151, v151
	v_rcp_f32_e32 v152, v152
	v_rcp_f32_e32 v153, v153
	v_pk_fma_f32 v[12:13], v[12:13], v[150:151], v[134:135]
	v_pk_fma_f32 v[14:15], v[14:15], v[152:153], v[136:137]
	s_nop 0
	v_cvt_pk_bf16_f32 v12, v12, v13
	v_cvt_pk_bf16_f32 v13, v14, v15
	global_store_dwordx2 v52, v[12:13], s[12:13] offset:0
	s_waitcnt vmcnt(4)
	v_lshlrev_b32_e32 v150, 16, v206
	v_and_b32_e32 v151, 0xffff0000, v206
	v_lshlrev_b32_e32 v152, 16, v207
	v_and_b32_e32 v153, 0xffff0000, v207
	v_pk_add_f32 v[150:151], v[58:59], v[150:151]
	v_pk_add_f32 v[152:153], v[60:61], v[152:153]
	s_nop 0
	v_mul_f32_e32 v150, 0xbfb8aa3b, v150
	v_mul_f32_e32 v151, 0xbfb8aa3b, v151
	v_mul_f32_e32 v152, 0xbfb8aa3b, v152
	v_mul_f32_e32 v153, 0xbfb8aa3b, v153
	v_exp_f32_e32 v150, v150
	v_exp_f32_e32 v151, v151
	v_exp_f32_e32 v152, v152
	v_exp_f32_e32 v153, v153
	v_add_f32_e32 v150, 1.0, v150
	v_add_f32_e32 v151, 1.0, v151
	v_add_f32_e32 v152, 1.0, v152
	v_add_f32_e32 v153, 1.0, v153
	v_rcp_f32_e32 v150, v150
	v_rcp_f32_e32 v151, v151
	v_rcp_f32_e32 v152, v152
	v_rcp_f32_e32 v153, v153
	v_pk_fma_f32 v[8:9], v[8:9], v[150:151], v[138:139]
	v_pk_fma_f32 v[10:11], v[10:11], v[152:153], v[140:141]
	s_nop 0
	v_cvt_pk_bf16_f32 v8, v8, v9
	v_cvt_pk_bf16_f32 v9, v10, v11
	global_store_dwordx2 v52, v[8:9], s[12:13] offset:32
	s_waitcnt vmcnt(2)
	v_lshlrev_b32_e32 v150, 16, v208
	v_and_b32_e32 v151, 0xffff0000, v208
	v_lshlrev_b32_e32 v152, 16, v209
	v_and_b32_e32 v153, 0xffff0000, v209
	v_pk_add_f32 v[150:151], v[62:63], v[150:151]
	v_pk_add_f32 v[152:153], v[64:65], v[152:153]
	s_nop 0
	v_mul_f32_e32 v150, 0xbfb8aa3b, v150
	v_mul_f32_e32 v151, 0xbfb8aa3b, v151
	v_mul_f32_e32 v152, 0xbfb8aa3b, v152
	v_mul_f32_e32 v153, 0xbfb8aa3b, v153
	v_exp_f32_e32 v150, v150
	v_exp_f32_e32 v151, v151
	v_exp_f32_e32 v152, v152
	v_exp_f32_e32 v153, v153
	v_add_f32_e32 v150, 1.0, v150
	v_add_f32_e32 v151, 1.0, v151
	v_add_f32_e32 v152, 1.0, v152
	v_add_f32_e32 v153, 1.0, v153
	v_rcp_f32_e32 v150, v150
	v_rcp_f32_e32 v151, v151
	v_rcp_f32_e32 v152, v152
	v_rcp_f32_e32 v153, v153
	v_pk_fma_f32 v[4:5], v[4:5], v[150:151], v[142:143]
	v_pk_fma_f32 v[6:7], v[6:7], v[152:153], v[144:145]
	s_nop 0
	v_cvt_pk_bf16_f32 v4, v4, v5
	v_cvt_pk_bf16_f32 v5, v6, v7
	global_store_dwordx2 v52, v[4:5], s[12:13] offset:64
	s_waitcnt vmcnt(0)
	v_lshlrev_b32_e32 v150, 16, v210
	v_and_b32_e32 v151, 0xffff0000, v210
	v_lshlrev_b32_e32 v152, 16, v211
	v_and_b32_e32 v153, 0xffff0000, v211
	v_pk_add_f32 v[150:151], v[66:67], v[150:151]
	v_pk_add_f32 v[152:153], v[68:69], v[152:153]
	s_nop 0
	v_mul_f32_e32 v150, 0xbfb8aa3b, v150
	v_mul_f32_e32 v151, 0xbfb8aa3b, v151
	v_mul_f32_e32 v152, 0xbfb8aa3b, v152
	v_mul_f32_e32 v153, 0xbfb8aa3b, v153
	v_exp_f32_e32 v150, v150
	v_exp_f32_e32 v151, v151
	v_exp_f32_e32 v152, v152
	v_exp_f32_e32 v153, v153
	v_add_f32_e32 v150, 1.0, v150
	v_add_f32_e32 v151, 1.0, v151
	v_add_f32_e32 v152, 1.0, v152
	v_add_f32_e32 v153, 1.0, v153
	v_rcp_f32_e32 v150, v150
	v_rcp_f32_e32 v151, v151
	v_rcp_f32_e32 v152, v152
	v_rcp_f32_e32 v153, v153
	v_pk_fma_f32 v[0:1], v[0:1], v[150:151], v[146:147]
	v_pk_fma_f32 v[2:3], v[2:3], v[152:153], v[148:149]
	s_nop 0
	v_cvt_pk_bf16_f32 v0, v0, v1
	v_cvt_pk_bf16_f32 v1, v2, v3
	global_store_dwordx2 v52, v[0:1], s[12:13] offset:96
	s_mov_b64 s[30:31], 0
	s_branch .LBB1_87
